# 7.2 barrier to first consumer: k-loop-exit barrier moved behind the LDS-free GEMM epilogues (to the next tile's prologue, before its first LDS-DMA); FFN-up keeps it in front of its LDS staging; split-
# speedup vs baseline: 1.0031x; 1.0031x over previous
.LBB0_623:
	s_barrier
	s_and_b64 vcc, exec, s[10:11]
	s_cbranch_vccz .LBB0_628
	v_readlane_b32 s2, v254, 3
	v_readlane_b32 s3, v255, 39
	s_add_i32 s8, s3, s2
	s_mul_i32 s34, s8, 0xb00
	s_lshl_b64 s[2:3], s[34:35], 1
	v_readlane_b32 s4, v255, 30
	v_readlane_b32 s5, v255, 31
	s_add_u32 s2, s4, s2
	s_addc_u32 s3, s5, s3
	v_readlane_b32 s5, v254, 4
	v_mov_b32_e32 v170, v163
	s_mul_i32 s4, s5, 0x1600
	v_readlane_b32 s6, v255, 32
	v_readlane_b32 s7, v255, 33
	v_ashrrev_i32_e32 v0, 6, v170
	s_waitcnt vmcnt(3)
	v_and_b32_e32 v2, 63, v170
	s_add_u32 s4, s6, s4
	s_mul_hi_i32 s5, s5, 0x1600
	s_waitcnt vmcnt(2)
	v_bfe_u32 v7, v170, 3, 3
	v_bfe_u32 v171, v170, 4, 2
	s_addc_u32 s5, s7, s5
	v_readlane_b32 s9, v255, 9
	v_lshlrev_b32_e32 v173, 4, v2
	v_lshl_or_b32 v2, v0, 5, v7
	v_xor_b32_e32 v4, v171, v170
	s_movk_i32 s24, 0xb00
	s_add_u32 s6, s2, s9
	v_mad_i64_i32 v[2:3], s[14:15], v2, s24, 0
	v_lshlrev_b32_e32 v4, 3, v4
	v_lshlrev_b32_e32 v174, 12, v0
	s_addc_u32 s7, s3, 0
	v_lshlrev_b64 v[164:165], 1, v[2:3]
	v_and_b32_e32 v4, 56, v4
	v_or_b32_e32 v8, v173, v174
	v_lshlrev_b32_e32 v6, 2, v0
	s_add_u32 s10, s4, s9
	v_lshl_add_u64 v[2:3], s[6:7], 0, v[164:165]
	s_waitcnt vmcnt(0)
	v_lshlrev_b32_e32 v130, 1, v4
	v_mov_b32_e32 v131, v1
	v_readfirstlane_b32 s9, v8
	v_add_u32_e32 v0, 0x8000, v8
	s_addc_u32 s11, s5, 0
	v_lshl_add_u64 v[2:3], v[2:3], 0, v[130:131]
	s_mov_b32 m0, s9
	v_readfirstlane_b32 s9, v0
	v_or_b32_e32 v0, 1, v6
	v_lshl_add_u64 v[4:5], s[10:11], 0, v[164:165]
	global_load_lds_dwordx4 v[2:3], off
	v_lshl_or_b32 v2, v0, 3, v7
	v_lshl_add_u64 v[4:5], v[4:5], 0, v[130:131]
	s_mov_b32 m0, s9
	v_lshrrev_b32_e32 v3, 1, v2
	global_load_lds_dwordx4 v[4:5], off
	v_xor_b32_e32 v4, v3, v170
	v_mad_i64_i32 v[2:3], s[14:15], v2, s24, 0
	v_lshlrev_b32_e32 v4, 3, v4
	v_lshlrev_b32_e32 v175, 10, v0
	v_lshlrev_b64 v[168:169], 1, v[2:3]
	v_and_b32_e32 v4, 56, v4
	v_or_b32_e32 v9, v173, v175
	v_lshl_add_u64 v[2:3], s[6:7], 0, v[168:169]
	v_lshlrev_b32_e32 v132, 1, v4
	v_mov_b32_e32 v133, v1
	v_readfirstlane_b32 s9, v9
	v_add_u32_e32 v0, 0x8000, v9
	v_or_b32_e32 v10, 2, v6
	v_lshl_add_u64 v[2:3], v[2:3], 0, v[132:133]
	v_lshl_add_u64 v[4:5], s[10:11], 0, v[168:169]
	s_mov_b32 m0, s9
	v_readfirstlane_b32 s9, v0
	v_lshl_or_b32 v0, v10, 3, v7
	v_lshl_add_u64 v[4:5], v[4:5], 0, v[132:133]
	global_load_lds_dwordx4 v[2:3], off
	s_mov_b32 m0, s9
	v_lshrrev_b32_e32 v2, 1, v0
	global_load_lds_dwordx4 v[4:5], off
	v_xor_b32_e32 v4, v2, v170
	v_mad_i64_i32 v[2:3], s[14:15], v0, s24, 0
	v_lshlrev_b32_e32 v0, 3, v4
	v_lshlrev_b32_e32 v176, 10, v10
	v_lshlrev_b64 v[154:155], 1, v[2:3]
	v_and_b32_e32 v0, 56, v0
	v_or_b32_e32 v10, v173, v176
	v_lshl_add_u64 v[2:3], s[6:7], 0, v[154:155]
	v_lshlrev_b32_e32 v0, 1, v0
	v_readfirstlane_b32 s9, v10
	v_lshl_add_u64 v[2:3], v[2:3], 0, v[0:1]
	s_mov_b32 m0, s9
	v_or_b32_e32 v6, 3, v6
	global_load_lds_dwordx4 v[2:3], off
	v_add_u32_e32 v2, 0x8000, v10
	v_lshl_add_u64 v[4:5], s[10:11], 0, v[154:155]
	v_readfirstlane_b32 s9, v2
	v_lshl_or_b32 v2, v6, 3, v7
	v_lshl_add_u64 v[4:5], v[4:5], 0, v[0:1]
	s_mov_b32 m0, s9
	v_lshrrev_b32_e32 v3, 1, v2
	global_load_lds_dwordx4 v[4:5], off
	v_xor_b32_e32 v4, v3, v170
	v_mad_i64_i32 v[2:3], s[14:15], v2, s24, 0
	v_lshlrev_b32_e32 v4, 3, v4
	v_lshlrev_b32_e32 v177, 10, v6
	v_lshlrev_b64 v[156:157], 1, v[2:3]
	v_and_b32_e32 v4, 56, v4
	v_or_b32_e32 v6, v173, v177
	v_lshl_add_u64 v[2:3], s[6:7], 0, v[156:157]
	v_lshlrev_b32_e32 v158, 1, v4
	v_mov_b32_e32 v159, v1
	v_readfirstlane_b32 s6, v6
	v_lshl_add_u64 v[2:3], v[2:3], 0, v[158:159]
	v_lshl_add_u64 v[4:5], s[10:11], 0, v[156:157]
	s_mov_b32 m0, s6
	v_readlane_b32 s10, v255, 10
	global_load_lds_dwordx4 v[2:3], off
	v_add_u32_e32 v2, 0x8000, v6
	v_readlane_b32 s11, v255, 11
	v_readfirstlane_b32 s6, v2
	v_lshl_add_u64 v[2:3], s[2:3], 0, v[164:165]
	s_mov_b32 s11, s35
	v_add_u32_e32 v6, 0x10000, v8
	v_lshl_add_u64 v[4:5], v[4:5], 0, v[158:159]
	s_mov_b32 m0, s6
	v_lshl_add_u64 v[2:3], v[2:3], 0, s[10:11]
	v_readfirstlane_b32 s6, v6
	global_load_lds_dwordx4 v[4:5], off
	v_lshl_add_u64 v[2:3], v[2:3], 0, v[130:131]
	s_mov_b32 m0, s6
	v_mov_b32_e32 v123, 0
	v_mov_b32_e32 v124, 0
	v_mov_b32_e32 v125, 0
	v_mov_b32_e32 v126, 0
	v_mov_b32_e32 v127, 0
	v_mov_b32_e32 v128, 0
	v_mov_b32_e32 v129, 0
	v_mov_b32_e32 v118, 0
	v_mov_b32_e32 v119, 0
	v_mov_b32_e32 v120, 0
	v_mov_b32_e32 v121, 0
	v_mov_b32_e32 v114, 0
	v_mov_b32_e32 v115, 0
	v_mov_b32_e32 v116, 0
	v_mov_b32_e32 v117, 0
	v_mov_b32_e32 v110, 0
	v_mov_b32_e32 v111, 0
	v_mov_b32_e32 v112, 0
	v_mov_b32_e32 v113, 0
	v_mov_b32_e32 v106, 0
	v_mov_b32_e32 v107, 0
	v_mov_b32_e32 v108, 0
	v_mov_b32_e32 v109, 0
	v_mov_b32_e32 v102, 0
	v_mov_b32_e32 v103, 0
	v_mov_b32_e32 v104, 0
	v_mov_b32_e32 v105, 0
	v_mov_b32_e32 v98, 0
	v_mov_b32_e32 v99, 0
	v_mov_b32_e32 v100, 0
	v_mov_b32_e32 v101, 0
	v_mov_b32_e32 v94, 0
	v_mov_b32_e32 v95, 0
	v_mov_b32_e32 v96, 0
	v_mov_b32_e32 v97, 0
	v_mov_b32_e32 v90, 0
	v_mov_b32_e32 v91, 0
	v_mov_b32_e32 v92, 0
	v_mov_b32_e32 v93, 0
	v_mov_b32_e32 v86, 0
	v_mov_b32_e32 v87, 0
	v_mov_b32_e32 v88, 0
	v_mov_b32_e32 v89, 0
	v_mov_b32_e32 v82, 0
	v_mov_b32_e32 v83, 0
	v_mov_b32_e32 v84, 0
	v_mov_b32_e32 v85, 0
	v_mov_b32_e32 v78, 0
	v_mov_b32_e32 v79, 0
	v_mov_b32_e32 v80, 0
	v_mov_b32_e32 v81, 0
	v_mov_b32_e32 v74, 0
	v_mov_b32_e32 v75, 0
	v_mov_b32_e32 v76, 0
	v_mov_b32_e32 v77, 0
	v_mov_b32_e32 v70, 0
	v_mov_b32_e32 v71, 0
	v_mov_b32_e32 v72, 0
	v_mov_b32_e32 v73, 0
	v_mov_b32_e32 v66, 0
	v_mov_b32_e32 v67, 0
	v_mov_b32_e32 v68, 0
	v_mov_b32_e32 v69, 0
	v_mov_b32_e32 v62, 0
	v_mov_b32_e32 v63, 0
	v_mov_b32_e32 v64, 0
	v_mov_b32_e32 v65, 0
	v_mov_b32_e32 v58, 0
	v_mov_b32_e32 v59, 0
	v_mov_b32_e32 v60, 0
	v_mov_b32_e32 v61, 0
	v_mov_b32_e32 v54, 0
	v_mov_b32_e32 v55, 0
	v_mov_b32_e32 v56, 0
	v_mov_b32_e32 v57, 0
	v_mov_b32_e32 v50, 0
	v_mov_b32_e32 v51, 0
	v_mov_b32_e32 v52, 0
	v_mov_b32_e32 v53, 0
	v_mov_b32_e32 v46, 0
	v_mov_b32_e32 v47, 0
	v_mov_b32_e32 v48, 0
	v_mov_b32_e32 v49, 0
	v_mov_b32_e32 v38, 0
	v_mov_b32_e32 v39, 0
	v_mov_b32_e32 v40, 0
	v_mov_b32_e32 v41, 0
	v_mov_b32_e32 v26, 0
	v_mov_b32_e32 v27, 0
	v_mov_b32_e32 v28, 0
	v_mov_b32_e32 v29, 0
	v_mov_b32_e32 v18, 0
	v_mov_b32_e32 v19, 0
	v_mov_b32_e32 v20, 0
	v_mov_b32_e32 v21, 0
	v_mov_b32_e32 v42, 0
	v_mov_b32_e32 v43, 0
	v_mov_b32_e32 v44, 0
	v_mov_b32_e32 v45, 0
	v_mov_b32_e32 v34, 0
	v_mov_b32_e32 v35, 0
	v_mov_b32_e32 v36, 0
	v_mov_b32_e32 v37, 0
	v_mov_b32_e32 v30, 0
	v_mov_b32_e32 v31, 0
	v_mov_b32_e32 v32, 0
	v_mov_b32_e32 v33, 0
	v_mov_b32_e32 v22, 0
	v_mov_b32_e32 v23, 0
	v_mov_b32_e32 v24, 0
	v_mov_b32_e32 v25, 0
	v_mov_b32_e32 v14, 0
	v_mov_b32_e32 v15, 0
	v_mov_b32_e32 v16, 0
	v_mov_b32_e32 v17, 0
	v_mov_b32_e32 v12, 0
	v_mov_b32_e32 v13, 0
	s_waitcnt vmcnt(0)
	s_waitcnt vmcnt(0) lgkmcnt(0)
	s_barrier
	global_load_lds_dwordx4 v[2:3], off
	v_add_u32_e32 v2, 0x18000, v8
	v_lshl_add_u64 v[4:5], s[4:5], 0, v[164:165]
	v_readfirstlane_b32 s6, v2
	s_mov_b32 m0, s6
	s_mov_b32 s6, s10
	v_lshl_add_u64 v[4:5], v[4:5], 0, s[10:11]
	v_lshl_add_u64 v[2:3], s[2:3], 0, v[168:169]
	v_writelane_b32 v255, s6, 10
	v_add_u32_e32 v6, 0x10000, v9
	v_lshl_add_u64 v[4:5], v[4:5], 0, v[130:131]
	v_lshl_add_u64 v[2:3], v[2:3], 0, s[10:11]
	v_writelane_b32 v255, s7, 11
	v_readfirstlane_b32 s6, v6
	global_load_lds_dwordx4 v[4:5], off
	v_lshl_add_u64 v[2:3], v[2:3], 0, v[132:133]
	s_mov_b32 m0, s6
	v_lshl_add_u64 v[4:5], s[4:5], 0, v[168:169]
	global_load_lds_dwordx4 v[2:3], off
	v_add_u32_e32 v2, 0x18000, v9
	v_lshl_add_u64 v[4:5], v[4:5], 0, s[10:11]
	v_readfirstlane_b32 s6, v2
	v_lshl_add_u64 v[4:5], v[4:5], 0, v[132:133]
	s_mov_b32 m0, s6
	v_and_b32_e32 v134, 15, v170
	global_load_lds_dwordx4 v[4:5], off
	v_ashrrev_i32_e32 v2, 1, v170
	s_movk_i32 s6, 0xff80
	v_and_or_b32 v172, v2, s6, v134
	v_readlane_b32 s6, v254, 6
	v_mov_b32_e32 v5, 0
	v_readlane_b32 s7, v254, 7
	s_andn2_b64 vcc, exec, s[6:7]
	s_cbranch_vccnz .Lgemm_skip_zero_b
	v_lshrrev_b32_e32 v10, 1, v134
	v_lshlrev_b32_e32 v2, 7, v170
	v_and_b32_e32 v179, 0x6780, v2
	v_xor_b32_e32 v2, v171, v10
	v_lshlrev_b32_e32 v178, 7, v172
	v_lshlrev_b32_e32 v180, 4, v2
	v_or_b32_e32 v11, v178, v180
	ds_read_b128 v[146:149], v11 offset:2048
	ds_read_b128 v[150:153], v11
	v_or_b32_e32 v11, v179, v180
	v_lshl_add_u64 v[2:3], s[4:5], 0, v[132:133]
	v_lshl_add_u64 v[4:5], s[2:3], 0, v[132:133]
	v_lshl_add_u64 v[6:7], s[4:5], 0, v[130:131]
	v_lshl_add_u64 v[8:9], s[2:3], 0, v[130:131]
	ds_read_b128 v[130:133], v11 offset:38912
	ds_read_b128 v[134:137], v11 offset:36864
	ds_read_b128 v[138:141], v11 offset:34816
	ds_read_b128 v[142:145], v11 offset:32768
	v_bitop3_b32 v10, v171, v10, 4 bitop3:0x36
	v_mov_b32_e32 v122, 0
	v_lshlrev_b32_e32 v181, 4, v10
	v_lshl_add_u64 v[160:161], v[8:9], 0, v[164:165]
	v_lshl_add_u64 v[164:165], v[6:7], 0, v[164:165]
	v_lshl_add_u64 v[166:167], v[4:5], 0, v[168:169]
	v_lshl_add_u64 v[168:169], v[2:3], 0, v[168:169]
	s_mov_b32 s9, 0
	v_readlane_b32 s6, v254, 5
	v_mov_b32_e32 v10, v122
	v_mov_b32_e32 v11, v122
	v_mov_b32_e32 v6, v122
	v_mov_b32_e32 v7, v122
	v_mov_b32_e32 v8, v122
	v_mov_b32_e32 v9, v122
	v_mov_b32_e32 v2, v122
	v_mov_b32_e32 v3, v122
	v_mov_b32_e32 v4, v122
	v_mov_b32_e32 v5, v122
	v_readlane_b32 s31, v254, 8
	v_readlane_b32 s38, v254, 9

.LBB0_637:
	s_and_b64 s[2:3], s[8:9], exec
	v_readlane_b32 s2, v255, 26
	v_readlane_b32 s4, v255, 30
	v_readlane_b32 s3, v255, 27
	v_readlane_b32 s5, v255, 31
	s_cselect_b32 s24, s5, s3
	s_cselect_b32 s28, s4, s2
	v_readlane_b32 s2, v255, 24
	v_readlane_b32 s4, v255, 32
	v_readlane_b32 s3, v255, 25
	v_readlane_b32 s5, v255, 33
	s_cselect_b32 s29, s5, s3
	s_cselect_b32 s34, s4, s2
	v_readlane_b32 s2, v255, 23
	v_readlane_b32 s3, v255, 43
	s_cselect_b32 s14, s3, s2
	v_readlane_b32 s2, v255, 39
	s_cselect_b32 s39, s2, 0
	v_readlane_b32 s2, v255, 18
	v_readlane_b32 s3, v255, 40
	s_cselect_b32 s44, s3, s2
	s_lshl_b32 s45, s15, 8
	s_mul_i32 s2, s15, 0xfe
	s_add_i32 s45, s45, s39
	s_lshl_b32 s6, s47, 8
	s_add_i32 s4, s2, -1
	s_cmp_gt_i32 s44, 6
	s_cbranch_scc1 .Lgemm_pro_nobar
	s_barrier
.Lgemm_pro_nobar:
	s_cmp_eq_u32 s44, 7
	s_cselect_b64 vcc, -1, 0
	s_and_b64 s[2:3], vcc, exec
	s_cselect_b32 s2, 0, s45
	s_cselect_b32 s40, s4, 0
	s_ashr_i32 s3, s2, 31
	v_mov_b32_e32 v175, v163
	s_mul_i32 s3, s3, s14
	s_mul_hi_u32 s4, s2, s14
	s_ashr_i32 s7, s6, 31
	s_add_i32 s3, s4, s3
	s_waitcnt vmcnt(1)
	v_ashrrev_i32_e32 v10, 6, v175
	s_waitcnt vmcnt(0)
	v_bfe_u32 v14, v175, 3, 3
	s_mul_i32 s2, s2, s14
	s_mul_i32 s4, s7, s14
	s_mul_hi_u32 s5, s6, s14
	v_lshl_or_b32 v6, v10, 5, v14
	s_add_i32 s5, s5, s4
	v_and_b32_e32 v0, 63, v175
	s_lshl_b64 s[2:3], s[2:3], 1
	s_mul_i32 s4, s6, s14
	s_add_u32 s2, s28, s2
	v_lshlrev_b32_e32 v176, 4, v0
	v_add_u32_e32 v0, s40, v6
	s_addc_u32 s3, s24, s3
	s_lshl_b64 s[4:5], s[4:5], 1
	v_med3_i32 v0, v0, 0, v211
	s_add_u32 s4, s34, s4
	v_cndmask_b32_e32 v0, v6, v0, vcc
	s_addc_u32 s5, s29, s5
	v_bfe_u32 v223, v175, 4, 2
	v_mad_u64_u32 v[166:167], s[28:29], v0, s14, 0
	v_xor_b32_e32 v4, v223, v175
	v_ashrrev_i32_e32 v2, 31, v0
	v_mov_b32_e32 v0, v167
	v_mad_u64_u32 v[2:3], s[28:29], v2, s14, v[0:1]
	v_lshlrev_b32_e32 v0, 3, v4
	v_lshlrev_b32_e32 v15, 2, v10
	v_and_b32_e32 v0, 56, v0
	v_lshlrev_b32_e32 v177, 12, v10
	v_lshlrev_b32_e32 v130, 1, v0
	v_ashrrev_i32_e32 v0, 31, v10
	v_or_b32_e32 v17, v176, v177
	v_or_b32_e32 v18, 1, v15
	v_and_b32_e32 v174, 3, v10
	v_mul_lo_u32 v16, v0, s14
	v_readfirstlane_b32 s15, v17
	v_add_u32_e32 v0, 0x8000, v17
	v_lshl_or_b32 v10, v18, 3, v14
	v_mov_b32_e32 v167, v2
	v_mad_u64_u32 v[168:169], s[28:29], v6, s14, 0
	s_mov_b32 m0, s15
	v_readfirstlane_b32 s15, v0
	v_add_u32_e32 v0, s40, v10
	v_lshl_add_u64 v[2:3], v[166:167], 1, s[2:3]
	v_mov_b32_e32 v131, v1
	v_add_u32_e32 v169, v169, v16
	v_med3_i32 v0, v0, 0, v211
	v_lshl_add_u64 v[4:5], v[2:3], 0, v[130:131]
	v_lshl_add_u64 v[6:7], v[168:169], 1, s[4:5]
	v_cndmask_b32_e32 v0, v10, v0, vcc
	v_lshl_add_u64 v[8:9], v[6:7], 0, v[130:131]
	global_load_lds_dwordx4 v[4:5], off
	s_mov_b32 m0, s15
	v_lshrrev_b32_e32 v4, 1, v10
	v_mad_u64_u32 v[170:171], s[28:29], v0, s14, 0
	global_load_lds_dwordx4 v[8:9], off
	v_xor_b32_e32 v8, v4, v175
	v_ashrrev_i32_e32 v4, 31, v0
	v_mov_b32_e32 v0, v171
	v_mad_u64_u32 v[4:5], s[28:29], v4, s14, v[0:1]
	v_lshlrev_b32_e32 v0, 3, v8
	v_lshlrev_b32_e32 v178, 10, v18
	v_mov_b32_e32 v171, v4
	v_and_b32_e32 v0, 56, v0
	v_mad_u64_u32 v[172:173], s[28:29], v10, s14, 0
	v_or_b32_e32 v18, v176, v178
	v_lshl_add_u64 v[4:5], v[170:171], 1, s[2:3]
	v_lshlrev_b32_e32 v132, 1, v0
	v_mov_b32_e32 v133, v1
	v_add_u32_e32 v173, v173, v16
	v_readfirstlane_b32 s15, v18
	v_add_u32_e32 v0, 0x8000, v18
	v_lshl_add_u64 v[8:9], v[4:5], 0, v[132:133]
	v_lshl_add_u64 v[10:11], v[172:173], 1, s[4:5]
	s_mov_b32 m0, s15
	v_readfirstlane_b32 s15, v0
	s_waitcnt lgkmcnt(0)
	v_lshl_add_u64 v[12:13], v[10:11], 0, v[132:133]
	global_load_lds_dwordx4 v[8:9], off
	s_mov_b32 m0, s15
	v_or_b32_e32 v19, 2, v15
	global_load_lds_dwordx4 v[12:13], off
	v_lshl_or_b32 v12, v19, 3, v14
	v_add_u32_e32 v0, s40, v12
	v_med3_i32 v0, v0, 0, v211
	v_cndmask_b32_e32 v0, v12, v0, vcc
	v_lshrrev_b32_e32 v8, 1, v12
	v_mad_u64_u32 v[154:155], s[28:29], v0, s14, 0
	v_xor_b32_e32 v13, v8, v175
	v_ashrrev_i32_e32 v8, 31, v0
	v_mov_b32_e32 v0, v155
	v_mad_u64_u32 v[8:9], s[28:29], v8, s14, v[0:1]
	v_lshlrev_b32_e32 v0, 3, v13
	v_lshlrev_b32_e32 v179, 10, v19
	v_mov_b32_e32 v155, v8
	v_and_b32_e32 v0, 56, v0
	v_or_b32_e32 v19, v176, v179
	v_lshl_add_u64 v[8:9], v[154:155], 1, s[2:3]
	v_lshlrev_b32_e32 v0, 1, v0
	v_readfirstlane_b32 s15, v19
	v_lshl_add_u64 v[8:9], v[8:9], 0, v[0:1]
	v_mad_u64_u32 v[156:157], s[28:29], v12, s14, 0
	s_mov_b32 m0, s15
	v_add_u32_e32 v157, v157, v16
	global_load_lds_dwordx4 v[8:9], off
	v_add_u32_e32 v8, 0x8000, v19
	v_lshl_add_u64 v[12:13], v[156:157], 1, s[4:5]
	v_readfirstlane_b32 s15, v8
	v_lshl_add_u64 v[12:13], v[12:13], 0, v[0:1]
	s_mov_b32 m0, s15
	v_or_b32_e32 v15, 3, v15
	global_load_lds_dwordx4 v[12:13], off
	v_lshl_or_b32 v12, v15, 3, v14
	v_add_u32_e32 v8, s40, v12
	v_med3_i32 v8, v8, 0, v211
	v_cndmask_b32_e32 v8, v12, v8, vcc
	v_lshrrev_b32_e32 v9, 1, v12
	v_mad_u64_u32 v[158:159], s[28:29], v8, s14, 0
	v_xor_b32_e32 v13, v9, v175
	v_ashrrev_i32_e32 v9, 31, v8
	v_mov_b32_e32 v8, v159
	v_mad_u64_u32 v[8:9], s[28:29], v9, s14, v[8:9]
	v_lshlrev_b32_e32 v13, 3, v13
	v_lshlrev_b32_e32 v180, 10, v15
	v_mov_b32_e32 v159, v8
	v_and_b32_e32 v13, 56, v13
	v_or_b32_e32 v14, v176, v180
	v_lshl_add_u64 v[8:9], v[158:159], 1, s[2:3]
	v_lshlrev_b32_e32 v160, 1, v13
	v_mov_b32_e32 v161, v1
	v_readfirstlane_b32 s15, v14
	v_lshl_add_u64 v[8:9], v[8:9], 0, v[160:161]
	v_mad_u64_u32 v[164:165], s[28:29], v12, s14, 0
	s_mov_b32 m0, s15
	v_add_u32_e32 v165, v165, v16
	global_load_lds_dwordx4 v[8:9], off
	v_add_u32_e32 v8, 0x8000, v14
	s_cmpk_gt_u32 s14, 0x7f
	v_lshl_add_u64 v[12:13], v[164:165], 1, s[4:5]
	v_readfirstlane_b32 s15, v8
	s_cselect_b32 s34, 0x80, 0
	v_add_u32_e32 v8, 0x10000, v17
	v_lshl_add_u64 v[12:13], v[12:13], 0, v[160:161]
	s_mov_b32 m0, s15
	v_lshl_add_u64 v[2:3], v[2:3], 0, s[34:35]
	v_readfirstlane_b32 s15, v8
	global_load_lds_dwordx4 v[12:13], off
	v_lshl_add_u64 v[2:3], v[2:3], 0, v[130:131]
	s_mov_b32 m0, s15
	v_mov_b32_e32 v127, 0
	v_mov_b32_e32 v128, 0
	v_mov_b32_e32 v129, 0
	v_mov_b32_e32 v122, 0
	v_mov_b32_e32 v123, 0
	v_mov_b32_e32 v124, 0
	v_mov_b32_e32 v125, 0
	v_mov_b32_e32 v118, 0
	v_mov_b32_e32 v119, 0
	v_mov_b32_e32 v120, 0
	v_mov_b32_e32 v121, 0
	v_mov_b32_e32 v114, 0
	v_mov_b32_e32 v115, 0
	v_mov_b32_e32 v116, 0
	v_mov_b32_e32 v117, 0
	v_mov_b32_e32 v110, 0
	v_mov_b32_e32 v111, 0
	v_mov_b32_e32 v112, 0
	v_mov_b32_e32 v113, 0
	v_mov_b32_e32 v106, 0
	v_mov_b32_e32 v107, 0
	v_mov_b32_e32 v108, 0
	v_mov_b32_e32 v109, 0
	v_mov_b32_e32 v102, 0
	v_mov_b32_e32 v103, 0
	v_mov_b32_e32 v104, 0
	v_mov_b32_e32 v105, 0
	v_mov_b32_e32 v98, 0
	v_mov_b32_e32 v99, 0
	v_mov_b32_e32 v100, 0
	v_mov_b32_e32 v101, 0
	v_mov_b32_e32 v94, 0
	v_mov_b32_e32 v95, 0
	v_mov_b32_e32 v96, 0
	v_mov_b32_e32 v97, 0
	v_mov_b32_e32 v90, 0
	v_mov_b32_e32 v91, 0
	v_mov_b32_e32 v92, 0
	v_mov_b32_e32 v93, 0
	v_mov_b32_e32 v86, 0
	v_mov_b32_e32 v87, 0
	v_mov_b32_e32 v88, 0
	v_mov_b32_e32 v89, 0
	v_mov_b32_e32 v82, 0
	v_mov_b32_e32 v83, 0
	v_mov_b32_e32 v84, 0
	v_mov_b32_e32 v85, 0
	v_mov_b32_e32 v78, 0
	v_mov_b32_e32 v79, 0
	v_mov_b32_e32 v80, 0
	v_mov_b32_e32 v81, 0
	v_mov_b32_e32 v74, 0
	v_mov_b32_e32 v75, 0
	v_mov_b32_e32 v76, 0
	v_mov_b32_e32 v77, 0
	v_mov_b32_e32 v70, 0
	v_mov_b32_e32 v71, 0
	v_mov_b32_e32 v72, 0
	v_mov_b32_e32 v73, 0
	v_mov_b32_e32 v66, 0
	v_mov_b32_e32 v67, 0
	v_mov_b32_e32 v68, 0
	v_mov_b32_e32 v69, 0
	v_mov_b32_e32 v62, 0
	v_mov_b32_e32 v63, 0
	v_mov_b32_e32 v64, 0
	v_mov_b32_e32 v65, 0
	v_mov_b32_e32 v58, 0
	v_mov_b32_e32 v59, 0
	v_mov_b32_e32 v60, 0
	v_mov_b32_e32 v61, 0
	v_mov_b32_e32 v54, 0
	v_mov_b32_e32 v55, 0
	v_mov_b32_e32 v56, 0
	v_mov_b32_e32 v57, 0
	v_mov_b32_e32 v50, 0
	v_mov_b32_e32 v51, 0
	v_mov_b32_e32 v52, 0
	v_mov_b32_e32 v53, 0
	v_mov_b32_e32 v46, 0
	v_mov_b32_e32 v47, 0
	v_mov_b32_e32 v48, 0
	v_mov_b32_e32 v49, 0
	v_mov_b32_e32 v42, 0
	v_mov_b32_e32 v43, 0
	v_mov_b32_e32 v44, 0
	v_mov_b32_e32 v45, 0
	v_mov_b32_e32 v34, 0
	v_mov_b32_e32 v35, 0
	v_mov_b32_e32 v36, 0
	v_mov_b32_e32 v37, 0
	v_mov_b32_e32 v30, 0
	v_mov_b32_e32 v31, 0
	v_mov_b32_e32 v32, 0
	v_mov_b32_e32 v33, 0
	v_mov_b32_e32 v38, 0
	v_mov_b32_e32 v39, 0
	v_mov_b32_e32 v40, 0
	v_mov_b32_e32 v41, 0
	v_mov_b32_e32 v26, 0
	v_mov_b32_e32 v27, 0
	v_mov_b32_e32 v28, 0
	v_mov_b32_e32 v29, 0
	v_mov_b32_e32 v22, 0
	v_mov_b32_e32 v23, 0
	v_mov_b32_e32 v24, 0
	v_mov_b32_e32 v25, 0
	v_mov_b32_e32 v19, 0
	v_mov_b32_e32 v20, 0
	v_mov_b32_e32 v21, 0
	v_mov_b32_e32 v14, 0
	v_mov_b32_e32 v15, 0
	v_mov_b32_e32 v16, 0
	v_mov_b32_e32 v12, 0
	v_mov_b32_e32 v13, 0
	s_waitcnt vmcnt(0)
	s_waitcnt vmcnt(0) lgkmcnt(0)
	s_barrier
	global_load_lds_dwordx4 v[2:3], off
	v_add_u32_e32 v2, 0x18000, v17
	v_lshl_add_u64 v[6:7], v[6:7], 0, s[34:35]
	v_readfirstlane_b32 s15, v2
	v_lshl_add_u64 v[6:7], v[6:7], 0, v[130:131]
	s_mov_b32 m0, s15
	v_lshl_add_u64 v[2:3], v[4:5], 0, s[34:35]
	global_load_lds_dwordx4 v[6:7], off
	v_add_u32_e32 v6, 0x10000, v18
	v_lshl_add_u64 v[2:3], v[2:3], 0, v[132:133]
	v_readfirstlane_b32 s15, v6
	s_mov_b32 m0, s15
	v_lshl_add_u64 v[4:5], v[10:11], 0, s[34:35]
	global_load_lds_dwordx4 v[2:3], off
	v_add_u32_e32 v2, 0x18000, v18
	v_lshl_add_u64 v[4:5], v[4:5], 0, v[132:133]
	v_readfirstlane_b32 s15, v2
	s_mov_b32 m0, s15
	v_and_b32_e32 v134, 15, v175
	global_load_lds_dwordx4 v[4:5], off
	v_ashrrev_i32_e32 v2, 1, v175
	s_movk_i32 s15, 0xff80
	v_mov_b32_e32 v5, 0
	v_and_or_b32 v225, v2, s15, v134
	v_lshlrev_b32_e32 v224, 6, v174
	s_cmp_lt_u32 s14, 64
	v_readlane_b32 s51, v255, 37
	v_readlane_b32 s52, v255, 38
	s_cbranch_scc1 .Lgemm_skip_zero_a
	v_lshrrev_b32_e32 v10, 1, v134
	v_or_b32_e32 v2, v224, v134
	v_lshlrev_b32_e32 v182, 7, v2
	v_xor_b32_e32 v2, v223, v10
	v_lshlrev_b32_e32 v181, 7, v225
	v_lshlrev_b32_e32 v183, 4, v2
	v_or_b32_e32 v11, v181, v183
	v_or_b32_e32 v244, v182, v183
	v_lshl_add_u32 v240, v166, 1, v130
	v_lshl_add_u32 v241, v168, 1, v130
	v_lshl_add_u32 v242, v170, 1, v132
	v_lshl_add_u32 v243, v172, 1, v132
	ds_read_b128 v[150:153], v11
	ds_read_b128 v[146:149], v11 offset:2048
	ds_read_b128 v[142:145], v244 offset:32768
	ds_read_b128 v[138:141], v244 offset:34816
	ds_read_b128 v[134:137], v244 offset:36864
	ds_read_b128 v[200:203], v11 offset:4096
	ds_read_b128 v[130:133], v244 offset:38912
	ds_read_b128 v[236:239], v11 offset:6144
	s_lshr_b32 s14, s14, 6
	v_bitop3_b32 v10, v223, v10, 4 bitop3:0x36
	v_mov_b32_e32 v126, 0
	s_add_i32 s15, s14, -1
	v_lshlrev_b32_e32 v184, 4, v10
	s_mov_b32 s24, 0
	s_mov_b32 s28, 0
	v_mov_b32_e32 v161, v1
	v_lshl_add_u64 v[154:155], v[154:155], 1, v[0:1]
	v_lshl_add_u64 v[156:157], v[156:157], 1, v[0:1]
	v_lshl_add_u64 v[158:159], v[158:159], 1, v[160:161]
	v_lshl_add_u64 v[164:165], v[164:165], 1, v[160:161]
	v_readfirstlane_b32 s100, v179
	v_readfirstlane_b32 s101, v180
	v_readfirstlane_b32 s32, v178
	v_readfirstlane_b32 s41, v177
	s_lshl_b32 s32, s32, 16
	s_or_b32 s32, s32, s41
	v_readfirstlane_b32 s41, v163
	s_bitcmp1_b32 s41, 8
	s_cbranch_scc0 .Lgemm_prio_done
	s_setprio 1

.LBB0_640:
	s_setprio 0
	s_and_b64 s[2:3], s[8:9], exec
	s_waitcnt vmcnt(0)
	v_readlane_b32 s2, v255, 15
	v_readlane_b32 s4, v255, 19
	v_readlane_b32 s3, v255, 16
	v_readlane_b32 s5, v255, 20
	s_cselect_b32 s42, s2, s4
	v_readlane_b32 s2, v255, 17
	s_cselect_b32 s28, s51, 0
	s_cselect_b32 s29, s52, 0
	s_cselect_b32 s43, s3, s5
	s_cselect_b32 s46, s2, 0
	s_cmp_lt_i32 s44, 4
	s_mov_b64 s[2:3], -1
	s_waitcnt vmcnt(0) lgkmcnt(0)
	s_cbranch_scc1 .LBB0_1047
	s_cmp_gt_i32 s44, 6
	s_cbranch_scc0 .Lgemm_epi_nobar
	s_barrier
.Lgemm_epi_nobar:
	s_cmp_lt_i32 s44, 6
	s_cbranch_scc1 .LBB0_1041
	s_cmp_gt_i32 s44, 6
	s_cbranch_scc0 .LBB0_654
	v_lshlrev_b32_e32 v244, 2, v175
	v_and_b32_e32 v244, 0x7c, v244
	v_lshl_or_b32 v244, s47, 7, v244
	v_lshlrev_b32_e32 v244, 2, v244
	v_readlane_b32 s100, v253, 61
	v_readlane_b32 s101, v253, 62
	s_mul_i32 s32, s28, 0x10800
	s_add_u32 s100, s100, s32
	s_mul_hi_u32 s32, s28, 0x10800
	s_addc_u32 s101, s101, s32
	v_readlane_b32 s4, v253, 63
	v_readlane_b32 s5, v254, 0
	s_mul_i32 s32, s28, 0x5800
	s_add_u32 s4, s4, s32
	s_mul_hi_u32 s32, s28, 0x5800
	s_addc_u32 s5, s5, s32
	v_add_u32_e32 v245, 0x5000, v244
	v_add_u32_e32 v246, 0xb000, v244
	v_add_u32_e32 v247, 0x8000, v244
	v_add_u32_e32 v226, 0xd000, v244
	v_add_u32_e32 v227, 0x2000, v244
	global_load_dwordx4 v[176:179], v244, s[100:101]
	global_load_dwordx4 v[180:183], v245, s[100:101] offset:2048
	global_load_dwordx4 v[184:187], v246, s[100:101]
	global_load_dwordx4 v[200:203], v227, s[100:101] offset:3072
	global_load_dwordx4 v[228:231], v247, s[100:101] offset:1024
	global_load_dwordx4 v[232:235], v226, s[100:101] offset:3072
	global_load_dwordx4 v[236:239], v244, s[4:5]
	global_load_dwordx4 v[240:243], v227, s[4:5] offset:3072
	s_movk_i32 s15, 0x210
	v_lshlrev_b32_e32 v0, 3, v223
	v_mul_lo_u32 v132, v225, s15
	v_cvt_pk_bf16_f32 v131, v128, v129
	v_cvt_pk_bf16_f32 v130, v126, v127
	v_add3_u32 v0, v224, v132, v0
	v_cvt_pk_bf16_f32 v133, v124, v125
	v_cvt_pk_bf16_f32 v132, v122, v123
	ds_write2_b64 v0, v[130:131], v[132:133] offset1:4
	v_cvt_pk_bf16_f32 v131, v120, v121
	v_cvt_pk_bf16_f32 v130, v118, v119
	v_cvt_pk_bf16_f32 v133, v116, v117
	v_cvt_pk_bf16_f32 v132, v114, v115
	ds_write2_b64 v0, v[130:131], v[132:133] offset0:32 offset1:36
	v_cvt_pk_bf16_f32 v131, v112, v113
	v_cvt_pk_bf16_f32 v130, v110, v111
	v_cvt_pk_bf16_f32 v133, v108, v109
	v_cvt_pk_bf16_f32 v132, v106, v107
	v_add_u32_e32 v134, 0x2000, v0
	ds_write2_b64 v134, v[130:131], v[132:133] offset0:32 offset1:36
	v_cvt_pk_bf16_f32 v131, v104, v105
	v_cvt_pk_bf16_f32 v130, v102, v103
	v_cvt_pk_bf16_f32 v133, v100, v101
	v_cvt_pk_bf16_f32 v132, v98, v99
	ds_write2_b64 v134, v[130:131], v[132:133] offset0:64 offset1:68
	v_cvt_pk_bf16_f32 v131, v96, v97
	v_cvt_pk_bf16_f32 v130, v94, v95
	v_cvt_pk_bf16_f32 v133, v92, v93
	v_cvt_pk_bf16_f32 v132, v90, v91
	v_add_u32_e32 v134, 0x4000, v0
	ds_write2_b64 v134, v[130:131], v[132:133] offset0:64 offset1:68
	v_cvt_pk_bf16_f32 v131, v88, v89
	v_cvt_pk_bf16_f32 v130, v86, v87
	v_cvt_pk_bf16_f32 v133, v84, v85
	v_cvt_pk_bf16_f32 v132, v82, v83
	ds_write2_b64 v134, v[130:131], v[132:133] offset0:96 offset1:100
	v_cvt_pk_bf16_f32 v131, v80, v81
	v_cvt_pk_bf16_f32 v130, v78, v79
	v_cvt_pk_bf16_f32 v133, v76, v77
	v_cvt_pk_bf16_f32 v132, v74, v75
	v_add_u32_e32 v134, 0x6000, v0
	ds_write2_b64 v134, v[130:131], v[132:133] offset0:96 offset1:100
	v_cvt_pk_bf16_f32 v131, v72, v73
	v_cvt_pk_bf16_f32 v130, v70, v71
	v_cvt_pk_bf16_f32 v133, v68, v69
	v_cvt_pk_bf16_f32 v132, v66, v67
	ds_write2_b64 v134, v[130:131], v[132:133] offset0:128 offset1:132
	v_cvt_pk_bf16_f32 v131, v64, v65
	v_cvt_pk_bf16_f32 v130, v62, v63
	v_cvt_pk_bf16_f32 v133, v60, v61
	v_cvt_pk_bf16_f32 v132, v58, v59
	v_add_u32_e32 v134, 0x8000, v0
	ds_write2_b64 v134, v[130:131], v[132:133] offset0:128 offset1:132
	v_cvt_pk_bf16_f32 v131, v56, v57
	v_cvt_pk_bf16_f32 v130, v54, v55
	v_cvt_pk_bf16_f32 v133, v52, v53
	v_cvt_pk_bf16_f32 v132, v50, v51
	ds_write2_b64 v134, v[130:131], v[132:133] offset0:160 offset1:164
	v_cvt_pk_bf16_f32 v131, v48, v49
	v_cvt_pk_bf16_f32 v130, v46, v47
	v_cvt_pk_bf16_f32 v133, v44, v45
	v_cvt_pk_bf16_f32 v132, v42, v43
	v_add_u32_e32 v134, 0xa000, v0
	ds_write2_b64 v134, v[130:131], v[132:133] offset0:160 offset1:164
	v_cvt_pk_bf16_f32 v131, v36, v37
	v_cvt_pk_bf16_f32 v130, v34, v35
	v_cvt_pk_bf16_f32 v133, v32, v33
	v_cvt_pk_bf16_f32 v132, v30, v31
	ds_write2_b64 v134, v[130:131], v[132:133] offset0:192 offset1:196
	v_cvt_pk_bf16_f32 v131, v40, v41
	v_cvt_pk_bf16_f32 v130, v38, v39
	v_cvt_pk_bf16_f32 v133, v28, v29
	v_cvt_pk_bf16_f32 v132, v26, v27
	v_add_u32_e32 v134, 0xc000, v0
	ds_write2_b64 v134, v[130:131], v[132:133] offset0:192 offset1:196
	v_cvt_pk_bf16_f32 v131, v24, v25
	v_cvt_pk_bf16_f32 v130, v22, v23
	v_cvt_pk_bf16_f32 v133, v20, v21
	v_cvt_pk_bf16_f32 v132, v18, v19
	ds_write2_b64 v134, v[130:131], v[132:133] offset0:224 offset1:228
	v_cvt_pk_bf16_f32 v131, v16, v17
	v_cvt_pk_bf16_f32 v130, v14, v15
	v_cvt_pk_bf16_f32 v133, v12, v13
	v_cvt_pk_bf16_f32 v132, v10, v11
	v_add_u32_e32 v134, 0xe000, v0
	ds_write2_b64 v134, v[130:131], v[132:133] offset0:224 offset1:228
	v_cvt_pk_bf16_f32 v131, v8, v9
	v_cvt_pk_bf16_f32 v130, v6, v7
	v_cvt_pk_bf16_f32 v133, v4, v5
	v_cvt_pk_bf16_f32 v132, v2, v3
	v_add_u32_e32 v0, 0xe800, v0
	ds_write2_b64 v0, v[130:131], v[132:133] offset1:4
	v_lshlrev_b32_e32 v0, 2, v175
	v_and_b32_e32 v0, 0x7c, v0
	s_mul_i32 s2, s28, 0x10800
	v_readlane_b32 s48, v253, 61
	v_lshl_or_b32 v164, s47, 7, v0
	s_mul_hi_u32 s3, s28, 0x10800
	v_readlane_b32 s49, v253, 62
	s_add_u32 s2, s48, s2
	v_ashrrev_i32_e32 v165, 31, v164
	s_addc_u32 s3, s49, s3
	v_lshlrev_b64 v[130:131], 2, v[164:165]
	v_lshl_add_u64 v[150:151], s[2:3], 0, v[130:131]
	s_movk_i32 s2, 0x5000
	v_add_co_u32_e32 v134, vcc, s2, v150
	s_mov_b32 s2, 0xb000
	s_nop 0
	v_addc_co_u32_e32 v135, vcc, 0, v151, vcc
	v_add_co_u32_e32 v138, vcc, s2, v150
	v_readlane_b32 s50, v253, 63
	s_nop 0
	v_addc_co_u32_e32 v139, vcc, 0, v151, vcc
	v_add_co_u32_e32 v142, vcc, s25, v150
	s_mul_i32 s4, s28, 0x5800
	s_nop 0
	v_addc_co_u32_e32 v143, vcc, 0, v151, vcc
	s_mov_b32 s2, 0x8000
	v_readlane_b32 s51, v254, 0
	s_mul_hi_u32 s5, s28, 0x5800
	s_add_u32 s4, s50, s4
	v_add_co_u32_e32 v146, vcc, s2, v150
	s_addc_u32 s5, s51, s5
	s_nop 0
	v_addc_co_u32_e32 v147, vcc, 0, v151, vcc
	s_mov_b32 s2, 0xd000
	s_waitcnt lgkmcnt(0)
	s_barrier
	v_lshl_add_u64 v[158:159], s[4:5], 0, v[130:131]
	s_waitcnt vmcnt(0)
	v_mov_b64_e32 v[130:131], v[176:177]
	v_mov_b64_e32 v[132:133], v[178:179]
	v_add_co_u32_e32 v150, vcc, s2, v150
	v_mov_b64_e32 v[134:135], v[180:181]
	v_mov_b64_e32 v[136:137], v[182:183]
	s_nop 0
	v_mov_b64_e32 v[138:139], v[184:185]
	v_mov_b64_e32 v[140:141], v[186:187]
	v_addc_co_u32_e32 v151, vcc, 0, v151, vcc
	v_mov_b64_e32 v[142:143], v[200:201]
	v_mov_b64_e32 v[144:145], v[202:203]
	s_nop 0
	v_mov_b64_e32 v[146:147], v[228:229]
	v_mov_b64_e32 v[148:149], v[230:231]
	s_nop 0
	v_mov_b64_e32 v[150:151], v[232:233]
	v_mov_b64_e32 v[152:153], v[234:235]
	s_nop 0
	v_mov_b64_e32 v[154:155], v[236:237]
	v_mov_b64_e32 v[156:157], v[238:239]
	v_add_co_u32_e32 v158, vcc, 0x2000, v158
	v_ashrrev_i32_e32 v0, 5, v175
	s_nop 0
	v_addc_co_u32_e32 v159, vcc, 0, v159, vcc
	v_mov_b64_e32 v[158:159], v[240:241]
	v_mov_b64_e32 v[160:161], v[242:243]
	v_readlane_b32 s2, v252, 32
	v_readlane_b32 s3, v252, 33
	v_mul_lo_u32 v166, v0, s15
	v_and_b32_e32 v167, 31, v175
	s_mov_b32 s14, 0
	v_lshl_add_u64 v[164:165], v[164:165], 1, s[2:3]
	v_lshl_add_u32 v166, v167, 3, v166
	v_add_u32_e32 v167, s40, v0
	s_waitcnt vmcnt(0)
	s_mov_b32 s14, 0x8800
	v_mul_u32_u24_e32 v63, 0x2100, v0
	v_and_b32_e32 v64, 31, v175
	v_lshl_add_u32 v63, v64, 3, v63
	v_lshlrev_b32_e32 v61, 4, v0
	v_add_u32_e32 v61, 1, v61
	v_add_u32_e32 v62, s40, v61
	s_mov_b32 s4, 0x78787879
	v_mul_hi_i32 v60, v62, s4
	v_lshrrev_b32_e32 v64, 31, v60
	v_ashrrev_i32_e32 v60, 11, v60
	v_add_u32_e32 v60, v60, v64
	v_mul_i32_i24_e32 v60, 0x1100, v60
	v_sub_u32_e32 v60, v62, v60
	s_movk_i32 s4, 0x1600
	v_mad_i64_i32 v[58:59], s[4:5], v62, s4, v[164:165]
	v_mov_b32_e32 v56, 0x1600
	v_mov_b32_e32 v57, 0
	ds_read2_b64 v[26:29], v63 offset1:32
	ds_read2_b64 v[68:71], v63 offset0:66 offset1:98
	s_waitcnt lgkmcnt(0)
	v_lshlrev_b32_e32 v2, 16, v26
	v_and_b32_e32 v3, 0xffff0000, v26
	v_lshlrev_b32_e32 v4, 16, v27
	v_and_b32_e32 v5, 0xffff0000, v27
	v_lshlrev_b32_e32 v14, 16, v28
	v_and_b32_e32 v15, 0xffff0000, v28
	v_lshlrev_b32_e32 v16, 16, v29
	v_and_b32_e32 v17, 0xffff0000, v29
	v_lshlrev_b32_e32 v6, 16, v68
	v_and_b32_e32 v7, 0xffff0000, v68
	v_lshlrev_b32_e32 v8, 16, v69
	v_and_b32_e32 v9, 0xffff0000, v69
	v_lshlrev_b32_e32 v18, 16, v70
	v_and_b32_e32 v19, 0xffff0000, v70
	v_lshlrev_b32_e32 v20, 16, v71
	v_and_b32_e32 v21, 0xffff0000, v71
	v_add_u32_e32 v63, 0x420, v63
	v_add_u32_e32 v64, -1, v60
	v_add_u32_e32 v65, 0xfffffeff, v60
	v_cmp_gt_u32_e32 vcc, 0xfef, v65
	s_mov_b64 s[4:5], vcc
	v_cmp_gt_u32_e32 vcc, 0xef, v64
	s_or_b64 s[4:5], s[4:5], vcc
	v_add_u32_e32 v64, 15, v62
	v_cmp_gt_i32_e32 vcc, s14, v64
	s_and_b64 s[4:5], s[4:5], vcc
	s_xor_b64 s[4:5], s[4:5], exec
	s_cmp_eq_u64 s[4:5], 0
	s_cbranch_scc0 .Lconv_slow
	v_cmp_gt_u32_e32 vcc, 15, v0
	s_mov_b32 s6, 0xbfb8aa3b
	ds_read2_b64 v[26:29], v63 offset1:32
	s_waitcnt lgkmcnt(0)
	v_lshlrev_b32_e32 v10, 16, v26
	v_and_b32_e32 v11, 0xffff0000, v26
	v_lshlrev_b32_e32 v12, 16, v27
	v_and_b32_e32 v13, 0xffff0000, v27
	v_lshlrev_b32_e32 v22, 16, v28
	v_and_b32_e32 v23, 0xffff0000, v28
	v_lshlrev_b32_e32 v24, 16, v29
	v_and_b32_e32 v25, 0xffff0000, v29
	v_add_u32_e32 v63, 0x210, v63
	ds_read2_b64 v[26:29], v63 offset1:32
	v_pk_fma_f32 v[30:31], v[146:147], v[18:19], v[158:159]
	v_pk_fma_f32 v[32:33], v[148:149], v[20:21], v[160:161]
	v_pk_fma_f32 v[34:35], v[134:135], v[6:7], v[154:155]
	v_pk_fma_f32 v[36:37], v[136:137], v[8:9], v[156:157]
	v_pk_fma_f32 v[30:31], v[142:143], v[14:15], v[30:31]
	v_pk_fma_f32 v[32:33], v[144:145], v[16:17], v[32:33]
	v_pk_fma_f32 v[34:35], v[130:131], v[2:3], v[34:35]
	v_pk_fma_f32 v[36:37], v[132:133], v[4:5], v[36:37]
	v_pk_fma_f32 v[30:31], v[150:151], v[22:23], v[30:31]
	v_pk_fma_f32 v[32:33], v[152:153], v[24:25], v[32:33]
	v_pk_fma_f32 v[34:35], v[138:139], v[10:11], v[34:35]
	v_pk_fma_f32 v[36:37], v[140:141], v[12:13], v[36:37]
	v_pk_mul_f32 v[42:43], v[30:31], s[6:7] op_sel_hi:[1,0]
	v_pk_mul_f32 v[44:45], v[32:33], s[6:7] op_sel_hi:[1,0]
	v_exp_f32_e32 v42, v42
	v_exp_f32_e32 v43, v43
	v_exp_f32_e32 v44, v44
	v_exp_f32_e32 v45, v45
	v_pk_add_f32 v[42:43], v[42:43], 1.0 op_sel_hi:[1,0]
	v_pk_add_f32 v[44:45], v[44:45], 1.0 op_sel_hi:[1,0]
	v_rcp_f32_e32 v46, v42
	v_rcp_f32_e32 v47, v43
	v_rcp_f32_e32 v48, v44
	v_rcp_f32_e32 v49, v45
	v_pk_mul_f32 v[46:47], v[30:31], v[46:47]
	v_pk_mul_f32 v[48:49], v[32:33], v[48:49]
	v_pk_mul_f32 v[34:35], v[34:35], v[46:47]
	v_pk_mul_f32 v[36:37], v[36:37], v[48:49]
	v_cvt_pk_bf16_f32 v66, v34, v35
	v_cvt_pk_bf16_f32 v67, v36, v37
	global_store_dwordx2 v[58:59], v[66:67], off
	v_lshl_add_u64 v[58:59], v[58:59], 0, v[56:57]
	s_waitcnt lgkmcnt(0)
	v_lshlrev_b32_e32 v2, 16, v26
	v_and_b32_e32 v3, 0xffff0000, v26
	v_lshlrev_b32_e32 v4, 16, v27
	v_and_b32_e32 v5, 0xffff0000, v27
	v_lshlrev_b32_e32 v14, 16, v28
	v_and_b32_e32 v15, 0xffff0000, v28
	v_lshlrev_b32_e32 v16, 16, v29
	v_and_b32_e32 v17, 0xffff0000, v29
	v_add_u32_e32 v63, 0x210, v63
	ds_read2_b64 v[26:29], v63 offset1:32
	v_pk_fma_f32 v[30:31], v[146:147], v[22:23], v[158:159]
	v_pk_fma_f32 v[32:33], v[148:149], v[24:25], v[160:161]
	v_pk_fma_f32 v[34:35], v[134:135], v[10:11], v[154:155]
	v_pk_fma_f32 v[36:37], v[136:137], v[12:13], v[156:157]
	v_pk_fma_f32 v[30:31], v[142:143], v[18:19], v[30:31]
	v_pk_fma_f32 v[32:33], v[144:145], v[20:21], v[32:33]
	v_pk_fma_f32 v[34:35], v[130:131], v[6:7], v[34:35]
	v_pk_fma_f32 v[36:37], v[132:133], v[8:9], v[36:37]
	v_pk_fma_f32 v[30:31], v[150:151], v[14:15], v[30:31]
	v_pk_fma_f32 v[32:33], v[152:153], v[16:17], v[32:33]
	v_pk_fma_f32 v[34:35], v[138:139], v[2:3], v[34:35]
	v_pk_fma_f32 v[36:37], v[140:141], v[4:5], v[36:37]
	v_pk_mul_f32 v[42:43], v[30:31], s[6:7] op_sel_hi:[1,0]
	v_pk_mul_f32 v[44:45], v[32:33], s[6:7] op_sel_hi:[1,0]
	v_exp_f32_e32 v42, v42
	v_exp_f32_e32 v43, v43
	v_exp_f32_e32 v44, v44
	v_exp_f32_e32 v45, v45
	v_pk_add_f32 v[42:43], v[42:43], 1.0 op_sel_hi:[1,0]
	v_pk_add_f32 v[44:45], v[44:45], 1.0 op_sel_hi:[1,0]
	v_rcp_f32_e32 v46, v42
	v_rcp_f32_e32 v47, v43
	v_rcp_f32_e32 v48, v44
	v_rcp_f32_e32 v49, v45
	v_pk_mul_f32 v[46:47], v[30:31], v[46:47]
	v_pk_mul_f32 v[48:49], v[32:33], v[48:49]
	v_pk_mul_f32 v[34:35], v[34:35], v[46:47]
	v_pk_mul_f32 v[36:37], v[36:37], v[48:49]
	v_cvt_pk_bf16_f32 v66, v34, v35
	v_cvt_pk_bf16_f32 v67, v36, v37
	global_store_dwordx2 v[58:59], v[66:67], off
	v_lshl_add_u64 v[58:59], v[58:59], 0, v[56:57]
	s_waitcnt lgkmcnt(0)
	v_lshlrev_b32_e32 v6, 16, v26
	v_and_b32_e32 v7, 0xffff0000, v26
	v_lshlrev_b32_e32 v8, 16, v27
	v_and_b32_e32 v9, 0xffff0000, v27
	v_lshlrev_b32_e32 v18, 16, v28
	v_and_b32_e32 v19, 0xffff0000, v28
	v_lshlrev_b32_e32 v20, 16, v29
	v_and_b32_e32 v21, 0xffff0000, v29
	v_add_u32_e32 v63, 0x210, v63
	ds_read2_b64 v[26:29], v63 offset1:32
	v_pk_fma_f32 v[30:31], v[146:147], v[14:15], v[158:159]
	v_pk_fma_f32 v[32:33], v[148:149], v[16:17], v[160:161]
	v_pk_fma_f32 v[34:35], v[134:135], v[2:3], v[154:155]
	v_pk_fma_f32 v[36:37], v[136:137], v[4:5], v[156:157]
	v_pk_fma_f32 v[30:31], v[142:143], v[22:23], v[30:31]
	v_pk_fma_f32 v[32:33], v[144:145], v[24:25], v[32:33]
	v_pk_fma_f32 v[34:35], v[130:131], v[10:11], v[34:35]
	v_pk_fma_f32 v[36:37], v[132:133], v[12:13], v[36:37]
	v_pk_fma_f32 v[30:31], v[150:151], v[18:19], v[30:31]
	v_pk_fma_f32 v[32:33], v[152:153], v[20:21], v[32:33]
	v_pk_fma_f32 v[34:35], v[138:139], v[6:7], v[34:35]
	v_pk_fma_f32 v[36:37], v[140:141], v[8:9], v[36:37]
	v_pk_mul_f32 v[42:43], v[30:31], s[6:7] op_sel_hi:[1,0]
	v_pk_mul_f32 v[44:45], v[32:33], s[6:7] op_sel_hi:[1,0]
	v_exp_f32_e32 v42, v42
	v_exp_f32_e32 v43, v43
	v_exp_f32_e32 v44, v44
	v_exp_f32_e32 v45, v45
	v_pk_add_f32 v[42:43], v[42:43], 1.0 op_sel_hi:[1,0]
	v_pk_add_f32 v[44:45], v[44:45], 1.0 op_sel_hi:[1,0]
	v_rcp_f32_e32 v46, v42
	v_rcp_f32_e32 v47, v43
	v_rcp_f32_e32 v48, v44
	v_rcp_f32_e32 v49, v45
	v_pk_mul_f32 v[46:47], v[30:31], v[46:47]
	v_pk_mul_f32 v[48:49], v[32:33], v[48:49]
	v_pk_mul_f32 v[34:35], v[34:35], v[46:47]
	v_pk_mul_f32 v[36:37], v[36:37], v[48:49]
	v_cvt_pk_bf16_f32 v66, v34, v35
	v_cvt_pk_bf16_f32 v67, v36, v37
	global_store_dwordx2 v[58:59], v[66:67], off
	v_lshl_add_u64 v[58:59], v[58:59], 0, v[56:57]
	s_waitcnt lgkmcnt(0)
	v_lshlrev_b32_e32 v10, 16, v26
	v_and_b32_e32 v11, 0xffff0000, v26
	v_lshlrev_b32_e32 v12, 16, v27
	v_and_b32_e32 v13, 0xffff0000, v27
	v_lshlrev_b32_e32 v22, 16, v28
	v_and_b32_e32 v23, 0xffff0000, v28
	v_lshlrev_b32_e32 v24, 16, v29
	v_and_b32_e32 v25, 0xffff0000, v29
	v_add_u32_e32 v63, 0x210, v63
	ds_read2_b64 v[26:29], v63 offset1:32
	v_pk_fma_f32 v[30:31], v[146:147], v[18:19], v[158:159]
	v_pk_fma_f32 v[32:33], v[148:149], v[20:21], v[160:161]
	v_pk_fma_f32 v[34:35], v[134:135], v[6:7], v[154:155]
	v_pk_fma_f32 v[36:37], v[136:137], v[8:9], v[156:157]
	v_pk_fma_f32 v[30:31], v[142:143], v[14:15], v[30:31]
	v_pk_fma_f32 v[32:33], v[144:145], v[16:17], v[32:33]
	v_pk_fma_f32 v[34:35], v[130:131], v[2:3], v[34:35]
	v_pk_fma_f32 v[36:37], v[132:133], v[4:5], v[36:37]
	v_pk_fma_f32 v[30:31], v[150:151], v[22:23], v[30:31]
	v_pk_fma_f32 v[32:33], v[152:153], v[24:25], v[32:33]
	v_pk_fma_f32 v[34:35], v[138:139], v[10:11], v[34:35]
	v_pk_fma_f32 v[36:37], v[140:141], v[12:13], v[36:37]
	v_pk_mul_f32 v[42:43], v[30:31], s[6:7] op_sel_hi:[1,0]
	v_pk_mul_f32 v[44:45], v[32:33], s[6:7] op_sel_hi:[1,0]
	v_exp_f32_e32 v42, v42
	v_exp_f32_e32 v43, v43
	v_exp_f32_e32 v44, v44
	v_exp_f32_e32 v45, v45
	v_pk_add_f32 v[42:43], v[42:43], 1.0 op_sel_hi:[1,0]
	v_pk_add_f32 v[44:45], v[44:45], 1.0 op_sel_hi:[1,0]
	v_rcp_f32_e32 v46, v42
	v_rcp_f32_e32 v47, v43
	v_rcp_f32_e32 v48, v44
	v_rcp_f32_e32 v49, v45
	v_pk_mul_f32 v[46:47], v[30:31], v[46:47]
	v_pk_mul_f32 v[48:49], v[32:33], v[48:49]
	v_pk_mul_f32 v[34:35], v[34:35], v[46:47]
	v_pk_mul_f32 v[36:37], v[36:37], v[48:49]
	v_cvt_pk_bf16_f32 v66, v34, v35
	v_cvt_pk_bf16_f32 v67, v36, v37
	global_store_dwordx2 v[58:59], v[66:67], off
	v_lshl_add_u64 v[58:59], v[58:59], 0, v[56:57]
	s_waitcnt lgkmcnt(0)
	v_lshlrev_b32_e32 v2, 16, v26
	v_and_b32_e32 v3, 0xffff0000, v26
	v_lshlrev_b32_e32 v4, 16, v27
	v_and_b32_e32 v5, 0xffff0000, v27
	v_lshlrev_b32_e32 v14, 16, v28
	v_and_b32_e32 v15, 0xffff0000, v28
	v_lshlrev_b32_e32 v16, 16, v29
	v_and_b32_e32 v17, 0xffff0000, v29
	v_add_u32_e32 v63, 0x210, v63
	ds_read2_b64 v[26:29], v63 offset1:32
	v_pk_fma_f32 v[30:31], v[146:147], v[22:23], v[158:159]
	v_pk_fma_f32 v[32:33], v[148:149], v[24:25], v[160:161]
	v_pk_fma_f32 v[34:35], v[134:135], v[10:11], v[154:155]
	v_pk_fma_f32 v[36:37], v[136:137], v[12:13], v[156:157]
	v_pk_fma_f32 v[30:31], v[142:143], v[18:19], v[30:31]
	v_pk_fma_f32 v[32:33], v[144:145], v[20:21], v[32:33]
	v_pk_fma_f32 v[34:35], v[130:131], v[6:7], v[34:35]
	v_pk_fma_f32 v[36:37], v[132:133], v[8:9], v[36:37]
	v_pk_fma_f32 v[30:31], v[150:151], v[14:15], v[30:31]
	v_pk_fma_f32 v[32:33], v[152:153], v[16:17], v[32:33]
	v_pk_fma_f32 v[34:35], v[138:139], v[2:3], v[34:35]
	v_pk_fma_f32 v[36:37], v[140:141], v[4:5], v[36:37]
	v_pk_mul_f32 v[42:43], v[30:31], s[6:7] op_sel_hi:[1,0]
	v_pk_mul_f32 v[44:45], v[32:33], s[6:7] op_sel_hi:[1,0]
	v_exp_f32_e32 v42, v42
	v_exp_f32_e32 v43, v43
	v_exp_f32_e32 v44, v44
	v_exp_f32_e32 v45, v45
	v_pk_add_f32 v[42:43], v[42:43], 1.0 op_sel_hi:[1,0]
	v_pk_add_f32 v[44:45], v[44:45], 1.0 op_sel_hi:[1,0]
	v_rcp_f32_e32 v46, v42
	v_rcp_f32_e32 v47, v43
	v_rcp_f32_e32 v48, v44
	v_rcp_f32_e32 v49, v45
	v_pk_mul_f32 v[46:47], v[30:31], v[46:47]
	v_pk_mul_f32 v[48:49], v[32:33], v[48:49]
	v_pk_mul_f32 v[34:35], v[34:35], v[46:47]
	v_pk_mul_f32 v[36:37], v[36:37], v[48:49]
	v_cvt_pk_bf16_f32 v66, v34, v35
	v_cvt_pk_bf16_f32 v67, v36, v37
	global_store_dwordx2 v[58:59], v[66:67], off
	v_lshl_add_u64 v[58:59], v[58:59], 0, v[56:57]
	s_waitcnt lgkmcnt(0)
	v_lshlrev_b32_e32 v6, 16, v26
	v_and_b32_e32 v7, 0xffff0000, v26
	v_lshlrev_b32_e32 v8, 16, v27
	v_and_b32_e32 v9, 0xffff0000, v27
	v_lshlrev_b32_e32 v18, 16, v28
	v_and_b32_e32 v19, 0xffff0000, v28
	v_lshlrev_b32_e32 v20, 16, v29
	v_and_b32_e32 v21, 0xffff0000, v29
	v_add_u32_e32 v63, 0x210, v63
	ds_read2_b64 v[26:29], v63 offset1:32
	v_pk_fma_f32 v[30:31], v[146:147], v[14:15], v[158:159]
	v_pk_fma_f32 v[32:33], v[148:149], v[16:17], v[160:161]
	v_pk_fma_f32 v[34:35], v[134:135], v[2:3], v[154:155]
	v_pk_fma_f32 v[36:37], v[136:137], v[4:5], v[156:157]
	v_pk_fma_f32 v[30:31], v[142:143], v[22:23], v[30:31]
	v_pk_fma_f32 v[32:33], v[144:145], v[24:25], v[32:33]
	v_pk_fma_f32 v[34:35], v[130:131], v[10:11], v[34:35]
	v_pk_fma_f32 v[36:37], v[132:133], v[12:13], v[36:37]
	v_pk_fma_f32 v[30:31], v[150:151], v[18:19], v[30:31]
	v_pk_fma_f32 v[32:33], v[152:153], v[20:21], v[32:33]
	v_pk_fma_f32 v[34:35], v[138:139], v[6:7], v[34:35]
	v_pk_fma_f32 v[36:37], v[140:141], v[8:9], v[36:37]
	v_pk_mul_f32 v[42:43], v[30:31], s[6:7] op_sel_hi:[1,0]
	v_pk_mul_f32 v[44:45], v[32:33], s[6:7] op_sel_hi:[1,0]
	v_exp_f32_e32 v42, v42
	v_exp_f32_e32 v43, v43
	v_exp_f32_e32 v44, v44
	v_exp_f32_e32 v45, v45
	v_pk_add_f32 v[42:43], v[42:43], 1.0 op_sel_hi:[1,0]
	v_pk_add_f32 v[44:45], v[44:45], 1.0 op_sel_hi:[1,0]
	v_rcp_f32_e32 v46, v42
	v_rcp_f32_e32 v47, v43
	v_rcp_f32_e32 v48, v44
	v_rcp_f32_e32 v49, v45
	v_pk_mul_f32 v[46:47], v[30:31], v[46:47]
	v_pk_mul_f32 v[48:49], v[32:33], v[48:49]
	v_pk_mul_f32 v[34:35], v[34:35], v[46:47]
	v_pk_mul_f32 v[36:37], v[36:37], v[48:49]
	v_cvt_pk_bf16_f32 v66, v34, v35
	v_cvt_pk_bf16_f32 v67, v36, v37
	global_store_dwordx2 v[58:59], v[66:67], off
	v_lshl_add_u64 v[58:59], v[58:59], 0, v[56:57]
	s_waitcnt lgkmcnt(0)
	v_lshlrev_b32_e32 v10, 16, v26
	v_and_b32_e32 v11, 0xffff0000, v26
	v_lshlrev_b32_e32 v12, 16, v27
	v_and_b32_e32 v13, 0xffff0000, v27
	v_lshlrev_b32_e32 v22, 16, v28
	v_and_b32_e32 v23, 0xffff0000, v28
	v_lshlrev_b32_e32 v24, 16, v29
	v_and_b32_e32 v25, 0xffff0000, v29
	v_add_u32_e32 v63, 0x210, v63
	ds_read2_b64 v[26:29], v63 offset1:32
	v_pk_fma_f32 v[30:31], v[146:147], v[18:19], v[158:159]
	v_pk_fma_f32 v[32:33], v[148:149], v[20:21], v[160:161]
	v_pk_fma_f32 v[34:35], v[134:135], v[6:7], v[154:155]
	v_pk_fma_f32 v[36:37], v[136:137], v[8:9], v[156:157]
	v_pk_fma_f32 v[30:31], v[142:143], v[14:15], v[30:31]
	v_pk_fma_f32 v[32:33], v[144:145], v[16:17], v[32:33]
	v_pk_fma_f32 v[34:35], v[130:131], v[2:3], v[34:35]
	v_pk_fma_f32 v[36:37], v[132:133], v[4:5], v[36:37]
	v_pk_fma_f32 v[30:31], v[150:151], v[22:23], v[30:31]
	v_pk_fma_f32 v[32:33], v[152:153], v[24:25], v[32:33]
	v_pk_fma_f32 v[34:35], v[138:139], v[10:11], v[34:35]
	v_pk_fma_f32 v[36:37], v[140:141], v[12:13], v[36:37]
	v_pk_mul_f32 v[42:43], v[30:31], s[6:7] op_sel_hi:[1,0]
	v_pk_mul_f32 v[44:45], v[32:33], s[6:7] op_sel_hi:[1,0]
	v_exp_f32_e32 v42, v42
	v_exp_f32_e32 v43, v43
	v_exp_f32_e32 v44, v44
	v_exp_f32_e32 v45, v45
	v_pk_add_f32 v[42:43], v[42:43], 1.0 op_sel_hi:[1,0]
	v_pk_add_f32 v[44:45], v[44:45], 1.0 op_sel_hi:[1,0]
	v_rcp_f32_e32 v46, v42
	v_rcp_f32_e32 v47, v43
	v_rcp_f32_e32 v48, v44
	v_rcp_f32_e32 v49, v45
	v_pk_mul_f32 v[46:47], v[30:31], v[46:47]
	v_pk_mul_f32 v[48:49], v[32:33], v[48:49]
	v_pk_mul_f32 v[34:35], v[34:35], v[46:47]
	v_pk_mul_f32 v[36:37], v[36:37], v[48:49]
	v_cvt_pk_bf16_f32 v66, v34, v35
	v_cvt_pk_bf16_f32 v67, v36, v37
	global_store_dwordx2 v[58:59], v[66:67], off
	v_lshl_add_u64 v[58:59], v[58:59], 0, v[56:57]
	s_waitcnt lgkmcnt(0)
	v_lshlrev_b32_e32 v2, 16, v26
	v_and_b32_e32 v3, 0xffff0000, v26
	v_lshlrev_b32_e32 v4, 16, v27
	v_and_b32_e32 v5, 0xffff0000, v27
	v_lshlrev_b32_e32 v14, 16, v28
	v_and_b32_e32 v15, 0xffff0000, v28
	v_lshlrev_b32_e32 v16, 16, v29
	v_and_b32_e32 v17, 0xffff0000, v29
	v_add_u32_e32 v63, 0x210, v63
	ds_read2_b64 v[26:29], v63 offset1:32
	v_pk_fma_f32 v[30:31], v[146:147], v[22:23], v[158:159]
	v_pk_fma_f32 v[32:33], v[148:149], v[24:25], v[160:161]
	v_pk_fma_f32 v[34:35], v[134:135], v[10:11], v[154:155]
	v_pk_fma_f32 v[36:37], v[136:137], v[12:13], v[156:157]
	v_pk_fma_f32 v[30:31], v[142:143], v[18:19], v[30:31]
	v_pk_fma_f32 v[32:33], v[144:145], v[20:21], v[32:33]
	v_pk_fma_f32 v[34:35], v[130:131], v[6:7], v[34:35]
	v_pk_fma_f32 v[36:37], v[132:133], v[8:9], v[36:37]
	v_pk_fma_f32 v[30:31], v[150:151], v[14:15], v[30:31]
	v_pk_fma_f32 v[32:33], v[152:153], v[16:17], v[32:33]
	v_pk_fma_f32 v[34:35], v[138:139], v[2:3], v[34:35]
	v_pk_fma_f32 v[36:37], v[140:141], v[4:5], v[36:37]
	v_pk_mul_f32 v[42:43], v[30:31], s[6:7] op_sel_hi:[1,0]
	v_pk_mul_f32 v[44:45], v[32:33], s[6:7] op_sel_hi:[1,0]
	v_exp_f32_e32 v42, v42
	v_exp_f32_e32 v43, v43
	v_exp_f32_e32 v44, v44
	v_exp_f32_e32 v45, v45
	v_pk_add_f32 v[42:43], v[42:43], 1.0 op_sel_hi:[1,0]
	v_pk_add_f32 v[44:45], v[44:45], 1.0 op_sel_hi:[1,0]
	v_rcp_f32_e32 v46, v42
	v_rcp_f32_e32 v47, v43
	v_rcp_f32_e32 v48, v44
	v_rcp_f32_e32 v49, v45
	v_pk_mul_f32 v[46:47], v[30:31], v[46:47]
	v_pk_mul_f32 v[48:49], v[32:33], v[48:49]
	v_pk_mul_f32 v[34:35], v[34:35], v[46:47]
	v_pk_mul_f32 v[36:37], v[36:37], v[48:49]
	v_cvt_pk_bf16_f32 v66, v34, v35
	v_cvt_pk_bf16_f32 v67, v36, v37
	global_store_dwordx2 v[58:59], v[66:67], off
	v_lshl_add_u64 v[58:59], v[58:59], 0, v[56:57]
	s_waitcnt lgkmcnt(0)
	v_lshlrev_b32_e32 v6, 16, v26
	v_and_b32_e32 v7, 0xffff0000, v26
	v_lshlrev_b32_e32 v8, 16, v27
	v_and_b32_e32 v9, 0xffff0000, v27
	v_lshlrev_b32_e32 v18, 16, v28
	v_and_b32_e32 v19, 0xffff0000, v28
	v_lshlrev_b32_e32 v20, 16, v29
	v_and_b32_e32 v21, 0xffff0000, v29
	v_add_u32_e32 v63, 0x210, v63
	ds_read2_b64 v[26:29], v63 offset1:32
	v_pk_fma_f32 v[30:31], v[146:147], v[14:15], v[158:159]
	v_pk_fma_f32 v[32:33], v[148:149], v[16:17], v[160:161]
	v_pk_fma_f32 v[34:35], v[134:135], v[2:3], v[154:155]
	v_pk_fma_f32 v[36:37], v[136:137], v[4:5], v[156:157]
	v_pk_fma_f32 v[30:31], v[142:143], v[22:23], v[30:31]
	v_pk_fma_f32 v[32:33], v[144:145], v[24:25], v[32:33]
	v_pk_fma_f32 v[34:35], v[130:131], v[10:11], v[34:35]
	v_pk_fma_f32 v[36:37], v[132:133], v[12:13], v[36:37]
	v_pk_fma_f32 v[30:31], v[150:151], v[18:19], v[30:31]
	v_pk_fma_f32 v[32:33], v[152:153], v[20:21], v[32:33]
	v_pk_fma_f32 v[34:35], v[138:139], v[6:7], v[34:35]
	v_pk_fma_f32 v[36:37], v[140:141], v[8:9], v[36:37]
	v_pk_mul_f32 v[42:43], v[30:31], s[6:7] op_sel_hi:[1,0]
	v_pk_mul_f32 v[44:45], v[32:33], s[6:7] op_sel_hi:[1,0]
	v_exp_f32_e32 v42, v42
	v_exp_f32_e32 v43, v43
	v_exp_f32_e32 v44, v44
	v_exp_f32_e32 v45, v45
	v_pk_add_f32 v[42:43], v[42:43], 1.0 op_sel_hi:[1,0]
	v_pk_add_f32 v[44:45], v[44:45], 1.0 op_sel_hi:[1,0]
	v_rcp_f32_e32 v46, v42
	v_rcp_f32_e32 v47, v43
	v_rcp_f32_e32 v48, v44
	v_rcp_f32_e32 v49, v45
	v_pk_mul_f32 v[46:47], v[30:31], v[46:47]
	v_pk_mul_f32 v[48:49], v[32:33], v[48:49]
	v_pk_mul_f32 v[34:35], v[34:35], v[46:47]
	v_pk_mul_f32 v[36:37], v[36:37], v[48:49]
	v_cvt_pk_bf16_f32 v66, v34, v35
	v_cvt_pk_bf16_f32 v67, v36, v37
	global_store_dwordx2 v[58:59], v[66:67], off
	v_lshl_add_u64 v[58:59], v[58:59], 0, v[56:57]
	s_waitcnt lgkmcnt(0)
	v_lshlrev_b32_e32 v10, 16, v26
	v_and_b32_e32 v11, 0xffff0000, v26
	v_lshlrev_b32_e32 v12, 16, v27
	v_and_b32_e32 v13, 0xffff0000, v27
	v_lshlrev_b32_e32 v22, 16, v28
	v_and_b32_e32 v23, 0xffff0000, v28
	v_lshlrev_b32_e32 v24, 16, v29
	v_and_b32_e32 v25, 0xffff0000, v29
	v_add_u32_e32 v63, 0x210, v63
	ds_read2_b64 v[26:29], v63 offset1:32
	v_pk_fma_f32 v[30:31], v[146:147], v[18:19], v[158:159]
	v_pk_fma_f32 v[32:33], v[148:149], v[20:21], v[160:161]
	v_pk_fma_f32 v[34:35], v[134:135], v[6:7], v[154:155]
	v_pk_fma_f32 v[36:37], v[136:137], v[8:9], v[156:157]
	v_pk_fma_f32 v[30:31], v[142:143], v[14:15], v[30:31]
	v_pk_fma_f32 v[32:33], v[144:145], v[16:17], v[32:33]
	v_pk_fma_f32 v[34:35], v[130:131], v[2:3], v[34:35]
	v_pk_fma_f32 v[36:37], v[132:133], v[4:5], v[36:37]
	v_pk_fma_f32 v[30:31], v[150:151], v[22:23], v[30:31]
	v_pk_fma_f32 v[32:33], v[152:153], v[24:25], v[32:33]
	v_pk_fma_f32 v[34:35], v[138:139], v[10:11], v[34:35]
	v_pk_fma_f32 v[36:37], v[140:141], v[12:13], v[36:37]
	v_pk_mul_f32 v[42:43], v[30:31], s[6:7] op_sel_hi:[1,0]
	v_pk_mul_f32 v[44:45], v[32:33], s[6:7] op_sel_hi:[1,0]
	v_exp_f32_e32 v42, v42
	v_exp_f32_e32 v43, v43
	v_exp_f32_e32 v44, v44
	v_exp_f32_e32 v45, v45
	v_pk_add_f32 v[42:43], v[42:43], 1.0 op_sel_hi:[1,0]
	v_pk_add_f32 v[44:45], v[44:45], 1.0 op_sel_hi:[1,0]
	v_rcp_f32_e32 v46, v42
	v_rcp_f32_e32 v47, v43
	v_rcp_f32_e32 v48, v44
	v_rcp_f32_e32 v49, v45
	v_pk_mul_f32 v[46:47], v[30:31], v[46:47]
	v_pk_mul_f32 v[48:49], v[32:33], v[48:49]
	v_pk_mul_f32 v[34:35], v[34:35], v[46:47]
	v_pk_mul_f32 v[36:37], v[36:37], v[48:49]
	v_cvt_pk_bf16_f32 v66, v34, v35
	v_cvt_pk_bf16_f32 v67, v36, v37
	global_store_dwordx2 v[58:59], v[66:67], off
	v_lshl_add_u64 v[58:59], v[58:59], 0, v[56:57]
	s_waitcnt lgkmcnt(0)
	v_lshlrev_b32_e32 v2, 16, v26
	v_and_b32_e32 v3, 0xffff0000, v26
	v_lshlrev_b32_e32 v4, 16, v27
	v_and_b32_e32 v5, 0xffff0000, v27
	v_lshlrev_b32_e32 v14, 16, v28
	v_and_b32_e32 v15, 0xffff0000, v28
	v_lshlrev_b32_e32 v16, 16, v29
	v_and_b32_e32 v17, 0xffff0000, v29
	v_add_u32_e32 v63, 0x210, v63
	ds_read2_b64 v[26:29], v63 offset1:32
	v_pk_fma_f32 v[30:31], v[146:147], v[22:23], v[158:159]
	v_pk_fma_f32 v[32:33], v[148:149], v[24:25], v[160:161]
	v_pk_fma_f32 v[34:35], v[134:135], v[10:11], v[154:155]
	v_pk_fma_f32 v[36:37], v[136:137], v[12:13], v[156:157]
	v_pk_fma_f32 v[30:31], v[142:143], v[18:19], v[30:31]
	v_pk_fma_f32 v[32:33], v[144:145], v[20:21], v[32:33]
	v_pk_fma_f32 v[34:35], v[130:131], v[6:7], v[34:35]
	v_pk_fma_f32 v[36:37], v[132:133], v[8:9], v[36:37]
	v_pk_fma_f32 v[30:31], v[150:151], v[14:15], v[30:31]
	v_pk_fma_f32 v[32:33], v[152:153], v[16:17], v[32:33]
	v_pk_fma_f32 v[34:35], v[138:139], v[2:3], v[34:35]
	v_pk_fma_f32 v[36:37], v[140:141], v[4:5], v[36:37]
	v_pk_mul_f32 v[42:43], v[30:31], s[6:7] op_sel_hi:[1,0]
	v_pk_mul_f32 v[44:45], v[32:33], s[6:7] op_sel_hi:[1,0]
	v_exp_f32_e32 v42, v42
	v_exp_f32_e32 v43, v43
	v_exp_f32_e32 v44, v44
	v_exp_f32_e32 v45, v45
	v_pk_add_f32 v[42:43], v[42:43], 1.0 op_sel_hi:[1,0]
	v_pk_add_f32 v[44:45], v[44:45], 1.0 op_sel_hi:[1,0]
	v_rcp_f32_e32 v46, v42
	v_rcp_f32_e32 v47, v43
	v_rcp_f32_e32 v48, v44
	v_rcp_f32_e32 v49, v45
	v_pk_mul_f32 v[46:47], v[30:31], v[46:47]
	v_pk_mul_f32 v[48:49], v[32:33], v[48:49]
	v_pk_mul_f32 v[34:35], v[34:35], v[46:47]
	v_pk_mul_f32 v[36:37], v[36:37], v[48:49]
	v_cvt_pk_bf16_f32 v66, v34, v35
	v_cvt_pk_bf16_f32 v67, v36, v37
	global_store_dwordx2 v[58:59], v[66:67], off
	v_lshl_add_u64 v[58:59], v[58:59], 0, v[56:57]
	s_waitcnt lgkmcnt(0)
	v_lshlrev_b32_e32 v6, 16, v26
	v_and_b32_e32 v7, 0xffff0000, v26
	v_lshlrev_b32_e32 v8, 16, v27
	v_and_b32_e32 v9, 0xffff0000, v27
	v_lshlrev_b32_e32 v18, 16, v28
	v_and_b32_e32 v19, 0xffff0000, v28
	v_lshlrev_b32_e32 v20, 16, v29
	v_and_b32_e32 v21, 0xffff0000, v29
	v_add_u32_e32 v63, 0x210, v63
	ds_read2_b64 v[26:29], v63 offset1:32
	v_pk_fma_f32 v[30:31], v[146:147], v[14:15], v[158:159]
	v_pk_fma_f32 v[32:33], v[148:149], v[16:17], v[160:161]
	v_pk_fma_f32 v[34:35], v[134:135], v[2:3], v[154:155]
	v_pk_fma_f32 v[36:37], v[136:137], v[4:5], v[156:157]
	v_pk_fma_f32 v[30:31], v[142:143], v[22:23], v[30:31]
	v_pk_fma_f32 v[32:33], v[144:145], v[24:25], v[32:33]
	v_pk_fma_f32 v[34:35], v[130:131], v[10:11], v[34:35]
	v_pk_fma_f32 v[36:37], v[132:133], v[12:13], v[36:37]
	v_pk_fma_f32 v[30:31], v[150:151], v[18:19], v[30:31]
	v_pk_fma_f32 v[32:33], v[152:153], v[20:21], v[32:33]
	v_pk_fma_f32 v[34:35], v[138:139], v[6:7], v[34:35]
	v_pk_fma_f32 v[36:37], v[140:141], v[8:9], v[36:37]
	v_pk_mul_f32 v[42:43], v[30:31], s[6:7] op_sel_hi:[1,0]
	v_pk_mul_f32 v[44:45], v[32:33], s[6:7] op_sel_hi:[1,0]
	v_exp_f32_e32 v42, v42
	v_exp_f32_e32 v43, v43
	v_exp_f32_e32 v44, v44
	v_exp_f32_e32 v45, v45
	v_pk_add_f32 v[42:43], v[42:43], 1.0 op_sel_hi:[1,0]
	v_pk_add_f32 v[44:45], v[44:45], 1.0 op_sel_hi:[1,0]
	v_rcp_f32_e32 v46, v42
	v_rcp_f32_e32 v47, v43
	v_rcp_f32_e32 v48, v44
	v_rcp_f32_e32 v49, v45
	v_pk_mul_f32 v[46:47], v[30:31], v[46:47]
	v_pk_mul_f32 v[48:49], v[32:33], v[48:49]
	v_pk_mul_f32 v[34:35], v[34:35], v[46:47]
	v_pk_mul_f32 v[36:37], v[36:37], v[48:49]
	v_cvt_pk_bf16_f32 v66, v34, v35
	v_cvt_pk_bf16_f32 v67, v36, v37
	global_store_dwordx2 v[58:59], v[66:67], off
	v_lshl_add_u64 v[58:59], v[58:59], 0, v[56:57]
	s_waitcnt lgkmcnt(0)
	v_lshlrev_b32_e32 v10, 16, v26
	v_and_b32_e32 v11, 0xffff0000, v26
	v_lshlrev_b32_e32 v12, 16, v27
	v_and_b32_e32 v13, 0xffff0000, v27
	v_lshlrev_b32_e32 v22, 16, v28
	v_and_b32_e32 v23, 0xffff0000, v28
	v_lshlrev_b32_e32 v24, 16, v29
	v_and_b32_e32 v25, 0xffff0000, v29
	v_add_u32_e32 v63, 0x210, v63
	ds_read2_b64 v[26:29], v63 offset1:32
	v_pk_fma_f32 v[30:31], v[146:147], v[18:19], v[158:159]
	v_pk_fma_f32 v[32:33], v[148:149], v[20:21], v[160:161]
	v_pk_fma_f32 v[34:35], v[134:135], v[6:7], v[154:155]
	v_pk_fma_f32 v[36:37], v[136:137], v[8:9], v[156:157]
	v_pk_fma_f32 v[30:31], v[142:143], v[14:15], v[30:31]
	v_pk_fma_f32 v[32:33], v[144:145], v[16:17], v[32:33]
	v_pk_fma_f32 v[34:35], v[130:131], v[2:3], v[34:35]
	v_pk_fma_f32 v[36:37], v[132:133], v[4:5], v[36:37]
	v_pk_fma_f32 v[30:31], v[150:151], v[22:23], v[30:31]
	v_pk_fma_f32 v[32:33], v[152:153], v[24:25], v[32:33]
	v_pk_fma_f32 v[34:35], v[138:139], v[10:11], v[34:35]
	v_pk_fma_f32 v[36:37], v[140:141], v[12:13], v[36:37]
	v_pk_mul_f32 v[42:43], v[30:31], s[6:7] op_sel_hi:[1,0]
	v_pk_mul_f32 v[44:45], v[32:33], s[6:7] op_sel_hi:[1,0]
	v_exp_f32_e32 v42, v42
	v_exp_f32_e32 v43, v43
	v_exp_f32_e32 v44, v44
	v_exp_f32_e32 v45, v45
	v_pk_add_f32 v[42:43], v[42:43], 1.0 op_sel_hi:[1,0]
	v_pk_add_f32 v[44:45], v[44:45], 1.0 op_sel_hi:[1,0]
	v_rcp_f32_e32 v46, v42
	v_rcp_f32_e32 v47, v43
	v_rcp_f32_e32 v48, v44
	v_rcp_f32_e32 v49, v45
	v_pk_mul_f32 v[46:47], v[30:31], v[46:47]
	v_pk_mul_f32 v[48:49], v[32:33], v[48:49]
	v_pk_mul_f32 v[34:35], v[34:35], v[46:47]
	v_pk_mul_f32 v[36:37], v[36:37], v[48:49]
	v_cvt_pk_bf16_f32 v66, v34, v35
	v_cvt_pk_bf16_f32 v67, v36, v37
	global_store_dwordx2 v[58:59], v[66:67], off
	v_lshl_add_u64 v[58:59], v[58:59], 0, v[56:57]
	s_waitcnt lgkmcnt(0)
	v_lshlrev_b32_e32 v2, 16, v26
	v_and_b32_e32 v3, 0xffff0000, v26
	v_lshlrev_b32_e32 v4, 16, v27
	v_and_b32_e32 v5, 0xffff0000, v27
	v_lshlrev_b32_e32 v14, 16, v28
	v_and_b32_e32 v15, 0xffff0000, v28
	v_lshlrev_b32_e32 v16, 16, v29
	v_and_b32_e32 v17, 0xffff0000, v29
	v_add_u32_e32 v63, 0x210, v63
	ds_read2_b64 v[26:29], v63 offset1:32
	v_pk_fma_f32 v[30:31], v[146:147], v[22:23], v[158:159]
	v_pk_fma_f32 v[32:33], v[148:149], v[24:25], v[160:161]
	v_pk_fma_f32 v[34:35], v[134:135], v[10:11], v[154:155]
	v_pk_fma_f32 v[36:37], v[136:137], v[12:13], v[156:157]
	v_pk_fma_f32 v[30:31], v[142:143], v[18:19], v[30:31]
	v_pk_fma_f32 v[32:33], v[144:145], v[20:21], v[32:33]
	v_pk_fma_f32 v[34:35], v[130:131], v[6:7], v[34:35]
	v_pk_fma_f32 v[36:37], v[132:133], v[8:9], v[36:37]
	v_pk_fma_f32 v[30:31], v[150:151], v[14:15], v[30:31]
	v_pk_fma_f32 v[32:33], v[152:153], v[16:17], v[32:33]
	v_pk_fma_f32 v[34:35], v[138:139], v[2:3], v[34:35]
	v_pk_fma_f32 v[36:37], v[140:141], v[4:5], v[36:37]
	v_pk_mul_f32 v[42:43], v[30:31], s[6:7] op_sel_hi:[1,0]
	v_pk_mul_f32 v[44:45], v[32:33], s[6:7] op_sel_hi:[1,0]
	v_exp_f32_e32 v42, v42
	v_exp_f32_e32 v43, v43
	v_exp_f32_e32 v44, v44
	v_exp_f32_e32 v45, v45
	v_pk_add_f32 v[42:43], v[42:43], 1.0 op_sel_hi:[1,0]
	v_pk_add_f32 v[44:45], v[44:45], 1.0 op_sel_hi:[1,0]
	v_rcp_f32_e32 v46, v42
	v_rcp_f32_e32 v47, v43
	v_rcp_f32_e32 v48, v44
	v_rcp_f32_e32 v49, v45
	v_pk_mul_f32 v[46:47], v[30:31], v[46:47]
	v_pk_mul_f32 v[48:49], v[32:33], v[48:49]
	v_pk_mul_f32 v[34:35], v[34:35], v[46:47]
	v_pk_mul_f32 v[36:37], v[36:37], v[48:49]
	v_cvt_pk_bf16_f32 v66, v34, v35
	v_cvt_pk_bf16_f32 v67, v36, v37
	global_store_dwordx2 v[58:59], v[66:67], off
	v_lshl_add_u64 v[58:59], v[58:59], 0, v[56:57]
	s_waitcnt lgkmcnt(0)
	v_lshlrev_b32_e32 v6, 16, v26
	v_and_b32_e32 v7, 0xffff0000, v26
	v_lshlrev_b32_e32 v8, 16, v27
	v_and_b32_e32 v9, 0xffff0000, v27
	v_lshlrev_b32_e32 v18, 16, v28
	v_and_b32_e32 v19, 0xffff0000, v28
	v_lshlrev_b32_e32 v20, 16, v29
	v_and_b32_e32 v21, 0xffff0000, v29
	v_add_u32_e32 v63, 0x210, v63
	ds_read2_b64 v[26:29], v63 offset1:32
	v_pk_fma_f32 v[30:31], v[146:147], v[14:15], v[158:159]
	v_pk_fma_f32 v[32:33], v[148:149], v[16:17], v[160:161]
	v_pk_fma_f32 v[34:35], v[134:135], v[2:3], v[154:155]
	v_pk_fma_f32 v[36:37], v[136:137], v[4:5], v[156:157]
	v_pk_fma_f32 v[30:31], v[142:143], v[22:23], v[30:31]
	v_pk_fma_f32 v[32:33], v[144:145], v[24:25], v[32:33]
	v_pk_fma_f32 v[34:35], v[130:131], v[10:11], v[34:35]
	v_pk_fma_f32 v[36:37], v[132:133], v[12:13], v[36:37]
	v_pk_fma_f32 v[30:31], v[150:151], v[18:19], v[30:31]
	v_pk_fma_f32 v[32:33], v[152:153], v[20:21], v[32:33]
	v_pk_fma_f32 v[34:35], v[138:139], v[6:7], v[34:35]
	v_pk_fma_f32 v[36:37], v[140:141], v[8:9], v[36:37]
	v_pk_mul_f32 v[42:43], v[30:31], s[6:7] op_sel_hi:[1,0]
	v_pk_mul_f32 v[44:45], v[32:33], s[6:7] op_sel_hi:[1,0]
	v_exp_f32_e32 v42, v42
	v_exp_f32_e32 v43, v43
	v_exp_f32_e32 v44, v44
	v_exp_f32_e32 v45, v45
	v_pk_add_f32 v[42:43], v[42:43], 1.0 op_sel_hi:[1,0]
	v_pk_add_f32 v[44:45], v[44:45], 1.0 op_sel_hi:[1,0]
	v_rcp_f32_e32 v46, v42
	v_rcp_f32_e32 v47, v43
	v_rcp_f32_e32 v48, v44
	v_rcp_f32_e32 v49, v45
	v_pk_mul_f32 v[46:47], v[30:31], v[46:47]
	v_pk_mul_f32 v[48:49], v[32:33], v[48:49]
	v_pk_mul_f32 v[34:35], v[34:35], v[46:47]
	v_pk_mul_f32 v[36:37], v[36:37], v[48:49]
	v_cvt_pk_bf16_f32 v66, v34, v35
	v_cvt_pk_bf16_f32 v67, v36, v37
	s_and_saveexec_b64 s[4:5], vcc
	global_store_dwordx2 v[58:59], v[66:67], off
	s_or_b64 exec, exec, s[4:5]
	v_lshl_add_u64 v[58:59], v[58:59], 0, v[56:57]
	s_waitcnt lgkmcnt(0)
	v_lshlrev_b32_e32 v10, 16, v26
	v_and_b32_e32 v11, 0xffff0000, v26
	v_lshlrev_b32_e32 v12, 16, v27
	v_and_b32_e32 v13, 0xffff0000, v27
	v_lshlrev_b32_e32 v22, 16, v28
	v_and_b32_e32 v23, 0xffff0000, v28
	v_lshlrev_b32_e32 v24, 16, v29
	v_and_b32_e32 v25, 0xffff0000, v29
	v_pk_fma_f32 v[30:31], v[146:147], v[18:19], v[158:159]
	v_pk_fma_f32 v[32:33], v[148:149], v[20:21], v[160:161]
	v_pk_fma_f32 v[34:35], v[134:135], v[6:7], v[154:155]
	v_pk_fma_f32 v[36:37], v[136:137], v[8:9], v[156:157]
	v_pk_fma_f32 v[30:31], v[142:143], v[14:15], v[30:31]
	v_pk_fma_f32 v[32:33], v[144:145], v[16:17], v[32:33]
	v_pk_fma_f32 v[34:35], v[130:131], v[2:3], v[34:35]
	v_pk_fma_f32 v[36:37], v[132:133], v[4:5], v[36:37]
	v_pk_fma_f32 v[30:31], v[150:151], v[22:23], v[30:31]
	v_pk_fma_f32 v[32:33], v[152:153], v[24:25], v[32:33]
	v_pk_fma_f32 v[34:35], v[138:139], v[10:11], v[34:35]
	v_pk_fma_f32 v[36:37], v[140:141], v[12:13], v[36:37]
	v_pk_mul_f32 v[42:43], v[30:31], s[6:7] op_sel_hi:[1,0]
	v_pk_mul_f32 v[44:45], v[32:33], s[6:7] op_sel_hi:[1,0]
	v_exp_f32_e32 v42, v42
	v_exp_f32_e32 v43, v43
	v_exp_f32_e32 v44, v44
	v_exp_f32_e32 v45, v45
	v_pk_add_f32 v[42:43], v[42:43], 1.0 op_sel_hi:[1,0]
	v_pk_add_f32 v[44:45], v[44:45], 1.0 op_sel_hi:[1,0]
	v_rcp_f32_e32 v46, v42
	v_rcp_f32_e32 v47, v43
	v_rcp_f32_e32 v48, v44
	v_rcp_f32_e32 v49, v45
	v_pk_mul_f32 v[46:47], v[30:31], v[46:47]
	v_pk_mul_f32 v[48:49], v[32:33], v[48:49]
	v_pk_mul_f32 v[34:35], v[34:35], v[46:47]
	v_pk_mul_f32 v[36:37], v[36:37], v[48:49]
	v_cvt_pk_bf16_f32 v66, v34, v35
	v_cvt_pk_bf16_f32 v67, v36, v37
	s_and_saveexec_b64 s[4:5], vcc
	global_store_dwordx2 v[58:59], v[66:67], off
	s_or_b64 exec, exec, s[4:5]
	v_lshl_add_u64 v[58:59], v[58:59], 0, v[56:57]
	s_branch .Lconv_done
